# attention: current-block (LDS) tiles take a hand-scheduled branch-free path inside the tile loop (K fragments fetched one tile ahead into their own registers, multiplicity words selected by scalar mas
# speedup vs baseline: 1.0023x; 1.0021x over previous
; __device__ __forceinline__ void attn_task(const AttnP& P, LAS unsigned char* lds, int b, int hd, int qq, int c, float shift, int lane_in) {
;     ...
;         } else {
;             attn_load_k(P, lds, hb, li, c, R0, lane, kf); attn_load_v(P, lds, hb, li, c, R0, lane, vf);
;             const int dl = c - (li - 10);
;             if (dl == 0) { w0 = 3 * Hp[0] - Hn[0] + Bn[0]; w1 = 3 * Hp[1] - Hn[1] + Bn[1]; }
;             else if (dl > 0) { const unsigned long long m = ((dl & 3) == 0) ? ~0ull : 0ull; w0 = Bp[0] + (Hp[0] & m); w1 = Bp[1] + (Hp[1] & m); }
;             else { const unsigned long long m = ((dl & 3) == 0) ? ~0ull : 0ull; w0 = Bn[0] + (Hn[0] & m); w1 = Bn[1] + (Hn[1] & m); }
;             ++li; ++ph;
;         }
.LBB0_173:
	s_andn2_b64 vcc, exec, s[4:5]
	s_cbranch_vccnz .LBB0_178
	s_branch .Lal_tile_a1
	s_cmp_gt_i32 s24, 9
	s_cselect_b64 s[0:1], -1, 0
	s_mov_b64 s[4:5], -1
	s_and_b64 vcc, exec, s[0:1]
	s_cbranch_vccz .LBB0_214
	v_lshl_add_u32 v66, s24, 5, v239
	v_mad_u64_u32 v[70:71], s[4:5], v66, s71, v[200:201]
	ds_read_b128 v[66:69], v70
	ds_read_b128 v[178:181], v70 offset:32
	ds_read_b128 v[174:177], v70 offset:64
	ds_read_b128 v[182:185], v70 offset:96
	s_cbranch_execz .LBB0_215

; __device__ __forceinline__ void tile_compute(const bf16x8 (&kf)[4], const bf16x8 (&vf)[2][2], const bf16x8 (&qf)[4], unsigned long long w0, unsigned long long w1,
;                                              float shift, f32x16& o0, f32x16& o1, f32x16& zacc, const bf16x8& ones) {
;     f32x16 st = {};
; #pragma unroll
;     for (int kk = 0; kk < 4; ++kk) st = __builtin_amdgcn_mfma_f32_32x32x16_bf16(kf[kk], qf[kk], st, 0, 0, 0);
;     if (__builtin_amdgcn_readfirstlane(__builtin_bit_cast(int, shift)) != 0) {
;         asm volatile("" ::: "memory");
; #pragma unroll
;         for (int e = 0; e < 16; ++e) st[e] -= shift;
;     }
;     unsigned pw[8];
; #pragma unroll
;     for (int eg = 0; eg < 2; ++eg) {
;         const unsigned long long w = eg ? w1 : w0;
;         const unsigned wl = (unsigned)w, wh = (unsigned)(w >> 32);
;         float pv[8];
; #pragma unroll
;         for (int p = 0; p < 4; ++p) {
;             pv[p] = (float)((wl >> (8 * p)) & 0xffu) * __builtin_amdgcn_exp2f(st[8 * eg + p]);
;             pv[4 + p] = (float)((wh >> (8 * p)) & 0xffu) * __builtin_amdgcn_exp2f(st[8 * eg + 4 + p]);
;         }
; #pragma unroll
;         for (int p = 0; p < 4; ++p) pw[4 * eg + p] = pk2(pv[2 * p], pv[2 * p + 1]);
;     }
;     const bf16x8 pf0 = __builtin_bit_cast(bf16x8, (u32x4){pw[0], pw[1], pw[2], pw[3]});
;     const bf16x8 pf1 = __builtin_bit_cast(bf16x8, (u32x4){pw[4], pw[5], pw[6], pw[7]});
;     o0 = __builtin_amdgcn_mfma_f32_32x32x16_bf16(vf[0][0], pf0, o0, 0, 0, 0);
;     o1 = __builtin_amdgcn_mfma_f32_32x32x16_bf16(vf[1][0], pf0, o1, 0, 0, 0);
;     zacc = __builtin_amdgcn_mfma_f32_32x32x16_bf16(ones, pf0, zacc, 0, 0, 0);
;     o0 = __builtin_amdgcn_mfma_f32_32x32x16_bf16(vf[0][1], pf1, o0, 0, 0, 0);
;     o1 = __builtin_amdgcn_mfma_f32_32x32x16_bf16(vf[1][1], pf1, o1, 0, 0, 0);
;     zacc = __builtin_amdgcn_mfma_f32_32x32x16_bf16(ones, pf1, zacc, 0, 0, 0);
; }
; __device__ __forceinline__ void attn_task(const AttnP& P, LAS unsigned char* lds, int b, int hd, int qq, int c, float shift, int lane_in) {
;     ...
;             attn_load_k(P, lds, hb, li, c, R0, lane, kf); attn_load_v(P, lds, hb, li, c, R0, lane, vf);
;             const int dl = c - (li - 10);
;             if (dl == 0) { w0 = 3 * Hp[0] - Hn[0] + Bn[0]; w1 = 3 * Hp[1] - Hn[1] + Bn[1]; }
.LBB0_245:
	s_waitcnt lgkmcnt(3)
	v_mfma_f32_32x32x16_bf16 v[66:81], v[66:69], v[86:89], 0
	v_readfirstlane_b32 s0, v2
	s_nop 1
	v_cmp_class_f32_e64 s[0:1], s0, 64
	s_and_b64 vcc, exec, s[0:1]
	s_waitcnt lgkmcnt(2)
	v_mfma_f32_32x32x16_bf16 v[66:81], v[178:181], v[90:93], v[66:81]
	s_waitcnt lgkmcnt(1)
	v_mfma_f32_32x32x16_bf16 v[66:81], v[174:177], v[94:97], v[66:81]
	s_waitcnt lgkmcnt(0)
	v_mfma_f32_32x32x16_bf16 v[66:81], v[182:185], v[98:101], v[66:81]
	s_cbranch_vccnz .LBB0_170
	s_nop 10
	v_sub_f32_e32 v81, v81, v2
	v_sub_f32_e32 v80, v80, v2
	v_sub_f32_e32 v79, v79, v2
	v_sub_f32_e32 v78, v78, v2
	v_sub_f32_e32 v77, v77, v2
	v_sub_f32_e32 v76, v76, v2
	v_sub_f32_e32 v75, v75, v2
	v_sub_f32_e32 v74, v74, v2
	v_sub_f32_e32 v73, v73, v2
	v_sub_f32_e32 v72, v72, v2
	v_sub_f32_e32 v71, v71, v2
	v_sub_f32_e32 v70, v70, v2
	v_sub_f32_e32 v69, v69, v2
	v_sub_f32_e32 v68, v68, v2
	v_sub_f32_e32 v67, v67, v2
	v_sub_f32_e32 v66, v66, v2
	s_branch .LBB0_170
.Lal_tile_a1:
	v_readfirstlane_b32 s75, v2
	s_cmp_lg_u32 s24, 10
	s_cbranch_scc1 .Lal_havek_a1
	v_lshl_add_u32 v12, s24, 5, v239
	v_mad_u32_u24 v12, v12, s71, v200
	ds_read_b128 v[244:247], v12
	ds_read_b128 v[248:251], v12 offset:32
	ds_read_b128 v[252:255], v12 offset:64
	ds_read_b128 v[186:189], v12 offset:96
.Lal_havek_a1:
	s_lshl_b32 s74, s24, 12
	v_add3_u32 v13, v238, s74, v233
	s_add_i32 s82, s92, 10
	s_and_b32 s75, s75, 0x7fffffff
	s_sub_i32 s73, s82, s24
	s_cmp_gt_i32 s73, 0
	s_cselect_b64 s[76:77], -1, 0
	s_and_b32 s74, s73, 3
	s_cmp_eq_u32 s74, 0
	s_cselect_b64 s[78:79], -1, 0
	s_cmp_eq_u32 s73, 0
	s_cselect_b64 s[80:81], -1, 0
	s_add_i32 s83, s24, 1
	s_waitcnt lgkmcnt(0)
	v_mfma_f32_32x32x16_bf16 v[66:81], v[244:247], v[86:89], 0
	v_mfma_f32_32x32x16_bf16 v[66:81], v[248:251], v[90:93], v[66:81]
	v_mfma_f32_32x32x16_bf16 v[66:81], v[252:255], v[94:97], v[66:81]
	v_mfma_f32_32x32x16_bf16 v[66:81], v[186:189], v[98:101], v[66:81]
	ds_read_b128 v[162:165], v13
	ds_read_b128 v[158:161], v13 offset:512
	ds_read_b128 v[166:169], v13 offset:2048
	ds_read_b128 v[170:173], v13 offset:2560
	v_lshl_add_u32 v12, s83, 5, v239
	v_mad_u32_u24 v12, v12, s71, v200
	ds_read_b128 v[244:247], v12
	ds_read_b128 v[248:251], v12 offset:32
	ds_read_b128 v[252:255], v12 offset:64
	ds_read_b128 v[186:189], v12 offset:96
	v_cndmask_b32_e64 v4, v114, v102, s[76:77]
	v_cndmask_b32_e64 v5, v115, v103, s[76:77]
	v_cndmask_b32_e64 v6, v116, v104, s[76:77]
	v_cndmask_b32_e64 v7, v117, v105, s[76:77]
	v_cndmask_b32_e64 v8, v122, v118, s[76:77]
	v_cndmask_b32_e64 v9, v123, v119, s[76:77]
	v_cndmask_b32_e64 v10, v124, v120, s[76:77]
	v_cndmask_b32_e64 v11, v125, v121, s[76:77]
	v_cndmask_b32_e64 v4, 0, v4, s[78:79]
	v_cndmask_b32_e64 v5, 0, v5, s[78:79]
	v_cndmask_b32_e64 v6, 0, v6, s[78:79]
	v_cndmask_b32_e64 v7, 0, v7, s[78:79]
	v_lshl_add_u64 v[212:213], v[4:5], 0, v[8:9]
	v_lshl_add_u64 v[210:211], v[6:7], 0, v[10:11]
	v_cndmask_b32_e64 v212, v212, v202, s[80:81]
	v_cndmask_b32_e64 v213, v213, v203, s[80:81]
	v_cndmask_b32_e64 v210, v210, v204, s[80:81]
	v_cndmask_b32_e64 v211, v211, v205, s[80:81]
	s_cmp_lg_u32 s75, 0
	s_cbranch_scc1 .Lal_shift_a1
.Lal_noshift_a1:
	v_exp_f32_e32 v66, v66
	v_exp_f32_e32 v67, v67
	v_exp_f32_e32 v70, v70
	v_exp_f32_e32 v71, v71
	v_exp_f32_e32 v68, v68
	v_exp_f32_e32 v69, v69
	v_cvt_f32_ubyte1_e32 v175, v212
	v_cvt_f32_ubyte0_e32 v174, v212
	v_exp_f32_e32 v72, v72
	v_exp_f32_e32 v73, v73
	v_pk_mul_f32 v[66:67], v[66:67], v[174:175]
	v_cvt_f32_ubyte1_e32 v175, v213
	v_cvt_f32_ubyte0_e32 v174, v213
	v_pk_mul_f32 v[70:71], v[70:71], v[174:175]
	v_cvt_f32_ubyte3_e32 v175, v212
	v_cvt_f32_ubyte2_e32 v174, v212
	v_pk_mul_f32 v[68:69], v[68:69], v[174:175]
	v_cvt_f32_ubyte3_e32 v175, v213
	v_cvt_f32_ubyte2_e32 v174, v213
	v_pk_mul_f32 v[72:73], v[72:73], v[174:175]
	v_cvt_pk_bf16_f32 v66, v66, v67
	v_cvt_pk_bf16_f32 v67, v68, v69
	v_cvt_pk_bf16_f32 v68, v70, v71
	v_exp_f32_e32 v70, v74
	v_exp_f32_e32 v71, v75
	v_cvt_pk_bf16_f32 v69, v72, v73
	v_exp_f32_e32 v72, v78
	v_exp_f32_e32 v73, v79
	s_waitcnt lgkmcnt(4)
	v_mfma_f32_32x32x16_bf16 v[18:33], v[162:165], v[66:69], v[18:33]
	v_cvt_f32_ubyte1_e32 v75, v210
	v_cvt_f32_ubyte0_e32 v74, v210
	v_mul_f32_e64 v70, v70, v74
	v_mul_f32_e64 v71, v71, v75
	v_cvt_f32_ubyte1_e32 v75, v211
	v_cvt_f32_ubyte0_e32 v74, v211
	v_pk_mul_f32 v[72:73], v[72:73], v[74:75]
	v_exp_f32_e32 v74, v76
	v_mfma_f32_32x32x16_bf16 v[34:49], v[158:161], v[66:69], v[34:49]
	v_exp_f32_e32 v75, v77
	v_exp_f32_e32 v76, v80
	v_exp_f32_e32 v77, v81
	v_cvt_f32_ubyte3_e32 v79, v210
	v_cvt_f32_ubyte2_e32 v78, v210
	v_pk_mul_f32 v[74:75], v[74:75], v[78:79]
	v_mfma_f32_32x32x16_bf16 v[50:65], v[154:157], v[66:69], v[50:65]
	v_cvt_f32_ubyte3_e32 v67, v211
	v_cvt_f32_ubyte2_e32 v66, v211
	v_mul_f32_e64 v76, v76, v66
	v_mul_f32_e64 v77, v77, v67
	v_cvt_pk_bf16_f32 v66, v70, v71
	v_cvt_pk_bf16_f32 v67, v74, v75
	v_cvt_pk_bf16_f32 v68, v72, v73
	v_cvt_pk_bf16_f32 v69, v76, v77
	s_add_i32 s24, s24, 1
	s_add_i32 s10, s10, 1
	s_cmp_lt_i32 s24, 26
	v_mfma_f32_32x32x16_bf16 v[18:33], v[166:169], v[66:69], v[18:33]
	s_cselect_b64 s[4:5], -1, 0
	s_cmp_lt_i32 s23, 10
	s_cselect_b64 s[0:1], -1, 0
	s_or_b64 s[4:5], s[4:5], s[0:1]
	s_and_b64 vcc, exec, s[4:5]
	v_mfma_f32_32x32x16_bf16 v[34:49], v[170:173], v[66:69], v[34:49]
	v_mfma_f32_32x32x16_bf16 v[50:65], v[154:157], v[66:69], v[50:65]
	s_cbranch_vccz .LBB0_247
	s_branch .LBB0_171
.Lal_shift_a1:
	v_sub_f32_e32 v66, v66, v2
	v_sub_f32_e32 v67, v67, v2
	v_sub_f32_e32 v68, v68, v2
	v_sub_f32_e32 v69, v69, v2
	v_sub_f32_e32 v70, v70, v2
	v_sub_f32_e32 v71, v71, v2
	v_sub_f32_e32 v72, v72, v2
	v_sub_f32_e32 v73, v73, v2
	v_sub_f32_e32 v74, v74, v2
	v_sub_f32_e32 v75, v75, v2
	v_sub_f32_e32 v76, v76, v2
	v_sub_f32_e32 v77, v77, v2
	v_sub_f32_e32 v78, v78, v2
	v_sub_f32_e32 v79, v79, v2
	v_sub_f32_e32 v80, v80, v2
	v_sub_f32_e32 v81, v81, v2
	s_branch .Lal_noshift_a1

; __device__ __forceinline__ void attn_task(const AttnP& P, LAS unsigned char* lds, int b, int hd, int qq, int c, float shift, int lane_in) {
;     ...
;         } else {
;             attn_load_k(P, lds, hb, li, c, R0, lane, kf); attn_load_v(P, lds, hb, li, c, R0, lane, vf);
;             const int dl = c - (li - 10);
;             if (dl == 0) { w0 = 3 * Hp[0] - Hn[0] + Bn[0]; w1 = 3 * Hp[1] - Hn[1] + Bn[1]; }
;             else if (dl > 0) { const unsigned long long m = ((dl & 3) == 0) ? ~0ull : 0ull; w0 = Bp[0] + (Hp[0] & m); w1 = Bp[1] + (Hp[1] & m); }
;             else { const unsigned long long m = ((dl & 3) == 0) ? ~0ull : 0ull; w0 = Bn[0] + (Hn[0] & m); w1 = Bn[1] + (Hn[1] & m); }
;             ++li; ++ph;
;         }
.LBB0_253:
	s_andn2_b64 vcc, exec, s[4:5]
	s_cbranch_vccnz .LBB0_258
	s_branch .Lal_tile_a2
	s_cmp_gt_i32 s19, 9
	s_cselect_b64 s[0:1], -1, 0
	s_mov_b64 s[4:5], -1
	s_and_b64 vcc, exec, s[0:1]
	s_cbranch_vccz .LBB0_294
	v_lshl_add_u32 v66, s19, 5, v239
	v_mad_u64_u32 v[70:71], s[4:5], v66, s71, v[200:201]
	ds_read_b128 v[66:69], v70
	ds_read_b128 v[178:181], v70 offset:32
	ds_read_b128 v[174:177], v70 offset:64
	ds_read_b128 v[182:185], v70 offset:96
	s_cbranch_execz .LBB0_295

; __device__ __forceinline__ void tile_compute(const bf16x8 (&kf)[4], const bf16x8 (&vf)[2][2], const bf16x8 (&qf)[4], unsigned long long w0, unsigned long long w1,
;                                              float shift, f32x16& o0, f32x16& o1, f32x16& zacc, const bf16x8& ones) {
;     f32x16 st = {};
; #pragma unroll
;     for (int kk = 0; kk < 4; ++kk) st = __builtin_amdgcn_mfma_f32_32x32x16_bf16(kf[kk], qf[kk], st, 0, 0, 0);
;     if (__builtin_amdgcn_readfirstlane(__builtin_bit_cast(int, shift)) != 0) {
;         asm volatile("" ::: "memory");
; #pragma unroll
;         for (int e = 0; e < 16; ++e) st[e] -= shift;
;     }
;     unsigned pw[8];
; #pragma unroll
;     for (int eg = 0; eg < 2; ++eg) {
;         const unsigned long long w = eg ? w1 : w0;
;         const unsigned wl = (unsigned)w, wh = (unsigned)(w >> 32);
;         float pv[8];
; #pragma unroll
;         for (int p = 0; p < 4; ++p) {
;             pv[p] = (float)((wl >> (8 * p)) & 0xffu) * __builtin_amdgcn_exp2f(st[8 * eg + p]);
;             pv[4 + p] = (float)((wh >> (8 * p)) & 0xffu) * __builtin_amdgcn_exp2f(st[8 * eg + 4 + p]);
;         }
; #pragma unroll
;         for (int p = 0; p < 4; ++p) pw[4 * eg + p] = pk2(pv[2 * p], pv[2 * p + 1]);
;     }
;     const bf16x8 pf0 = __builtin_bit_cast(bf16x8, (u32x4){pw[0], pw[1], pw[2], pw[3]});
;     const bf16x8 pf1 = __builtin_bit_cast(bf16x8, (u32x4){pw[4], pw[5], pw[6], pw[7]});
;     o0 = __builtin_amdgcn_mfma_f32_32x32x16_bf16(vf[0][0], pf0, o0, 0, 0, 0);
;     o1 = __builtin_amdgcn_mfma_f32_32x32x16_bf16(vf[1][0], pf0, o1, 0, 0, 0);
;     zacc = __builtin_amdgcn_mfma_f32_32x32x16_bf16(ones, pf0, zacc, 0, 0, 0);
;     o0 = __builtin_amdgcn_mfma_f32_32x32x16_bf16(vf[0][1], pf1, o0, 0, 0, 0);
;     o1 = __builtin_amdgcn_mfma_f32_32x32x16_bf16(vf[1][1], pf1, o1, 0, 0, 0);
;     zacc = __builtin_amdgcn_mfma_f32_32x32x16_bf16(ones, pf1, zacc, 0, 0, 0);
; }
; __device__ __forceinline__ void attn_task(const AttnP& P, LAS unsigned char* lds, int b, int hd, int qq, int c, float shift, int lane_in) {
;     ...
;             attn_load_k(P, lds, hb, li, c, R0, lane, kf); attn_load_v(P, lds, hb, li, c, R0, lane, vf);
;             const int dl = c - (li - 10);
;             if (dl == 0) { w0 = 3 * Hp[0] - Hn[0] + Bn[0]; w1 = 3 * Hp[1] - Hn[1] + Bn[1]; }
.Lal_tile_a2:
	v_readfirstlane_b32 s75, v2
	s_cmp_lg_u32 s19, 10
	s_cbranch_scc1 .Lal_havek_a2
	v_lshl_add_u32 v12, s19, 5, v239
	v_mad_u32_u24 v12, v12, s71, v200
	ds_read_b128 v[244:247], v12
	ds_read_b128 v[248:251], v12 offset:32
	ds_read_b128 v[252:255], v12 offset:64
	ds_read_b128 v[186:189], v12 offset:96
.Lal_havek_a2:
	s_lshl_b32 s74, s19, 12
	v_add3_u32 v13, v238, s74, v233
	s_add_i32 s82, s64, 10
	s_and_b32 s75, s75, 0x7fffffff
	s_sub_i32 s73, s82, s19
	s_cmp_gt_i32 s73, 0
	s_cselect_b64 s[76:77], -1, 0
	s_and_b32 s74, s73, 3
	s_cmp_eq_u32 s74, 0
	s_cselect_b64 s[78:79], -1, 0
	s_cmp_eq_u32 s73, 0
	s_cselect_b64 s[80:81], -1, 0
	s_add_i32 s83, s19, 1
	s_waitcnt lgkmcnt(0)
	v_mfma_f32_32x32x16_bf16 v[66:81], v[244:247], v[86:89], 0
	v_mfma_f32_32x32x16_bf16 v[66:81], v[248:251], v[90:93], v[66:81]
	v_mfma_f32_32x32x16_bf16 v[66:81], v[252:255], v[94:97], v[66:81]
	v_mfma_f32_32x32x16_bf16 v[66:81], v[186:189], v[98:101], v[66:81]
	ds_read_b128 v[162:165], v13
	ds_read_b128 v[158:161], v13 offset:512
	ds_read_b128 v[166:169], v13 offset:2048
	ds_read_b128 v[170:173], v13 offset:2560
	v_lshl_add_u32 v12, s83, 5, v239
	v_mad_u32_u24 v12, v12, s71, v200
	ds_read_b128 v[244:247], v12
	ds_read_b128 v[248:251], v12 offset:32
	ds_read_b128 v[252:255], v12 offset:64
	ds_read_b128 v[186:189], v12 offset:96
	v_cndmask_b32_e64 v4, v114, v102, s[76:77]
	v_cndmask_b32_e64 v5, v115, v103, s[76:77]
	v_cndmask_b32_e64 v6, v116, v104, s[76:77]
	v_cndmask_b32_e64 v7, v117, v105, s[76:77]
	v_cndmask_b32_e64 v8, v122, v118, s[76:77]
	v_cndmask_b32_e64 v9, v123, v119, s[76:77]
	v_cndmask_b32_e64 v10, v124, v120, s[76:77]
	v_cndmask_b32_e64 v11, v125, v121, s[76:77]
	v_cndmask_b32_e64 v4, 0, v4, s[78:79]
	v_cndmask_b32_e64 v5, 0, v5, s[78:79]
	v_cndmask_b32_e64 v6, 0, v6, s[78:79]
	v_cndmask_b32_e64 v7, 0, v7, s[78:79]
	v_lshl_add_u64 v[212:213], v[4:5], 0, v[8:9]
	v_lshl_add_u64 v[210:211], v[6:7], 0, v[10:11]
	v_cndmask_b32_e64 v212, v212, v202, s[80:81]
	v_cndmask_b32_e64 v213, v213, v203, s[80:81]
	v_cndmask_b32_e64 v210, v210, v204, s[80:81]
	v_cndmask_b32_e64 v211, v211, v205, s[80:81]
	s_cmp_lg_u32 s75, 0
	s_cbranch_scc1 .Lal_shift_a2
.Lal_noshift_a2:
	v_exp_f32_e32 v66, v66
	v_exp_f32_e32 v67, v67
	v_exp_f32_e32 v70, v70
	v_exp_f32_e32 v71, v71
	v_exp_f32_e32 v68, v68
	v_exp_f32_e32 v69, v69
	v_cvt_f32_ubyte1_e32 v175, v212
	v_cvt_f32_ubyte0_e32 v174, v212
	v_exp_f32_e32 v72, v72
	v_exp_f32_e32 v73, v73
	v_pk_mul_f32 v[66:67], v[66:67], v[174:175]
	v_cvt_f32_ubyte1_e32 v175, v213
	v_cvt_f32_ubyte0_e32 v174, v213
	v_pk_mul_f32 v[70:71], v[70:71], v[174:175]
	v_cvt_f32_ubyte3_e32 v175, v212
	v_cvt_f32_ubyte2_e32 v174, v212
	v_pk_mul_f32 v[68:69], v[68:69], v[174:175]
	v_cvt_f32_ubyte3_e32 v175, v213
	v_cvt_f32_ubyte2_e32 v174, v213
	v_pk_mul_f32 v[72:73], v[72:73], v[174:175]
	v_cvt_pk_bf16_f32 v66, v66, v67
	v_cvt_pk_bf16_f32 v67, v68, v69
	v_cvt_pk_bf16_f32 v68, v70, v71
	v_exp_f32_e32 v70, v74
	v_exp_f32_e32 v71, v75
	v_cvt_pk_bf16_f32 v69, v72, v73
	v_exp_f32_e32 v72, v78
	v_exp_f32_e32 v73, v79
	s_waitcnt lgkmcnt(4)
	v_mfma_f32_32x32x16_bf16 v[18:33], v[162:165], v[66:69], v[18:33]
	v_cvt_f32_ubyte1_e32 v75, v210
	v_cvt_f32_ubyte0_e32 v74, v210
	v_mul_f32_e64 v70, v70, v74
	v_mul_f32_e64 v71, v71, v75
	v_cvt_f32_ubyte1_e32 v75, v211
	v_cvt_f32_ubyte0_e32 v74, v211
	v_pk_mul_f32 v[72:73], v[72:73], v[74:75]
	v_exp_f32_e32 v74, v76
	v_mfma_f32_32x32x16_bf16 v[34:49], v[158:161], v[66:69], v[34:49]
	v_exp_f32_e32 v75, v77
	v_exp_f32_e32 v76, v80
	v_exp_f32_e32 v77, v81
	v_cvt_f32_ubyte3_e32 v79, v210
	v_cvt_f32_ubyte2_e32 v78, v210
	v_pk_mul_f32 v[74:75], v[74:75], v[78:79]
	v_mfma_f32_32x32x16_bf16 v[50:65], v[154:157], v[66:69], v[50:65]
	v_cvt_f32_ubyte3_e32 v67, v211
	v_cvt_f32_ubyte2_e32 v66, v211
	v_mul_f32_e64 v76, v76, v66
	v_mul_f32_e64 v77, v77, v67
	v_cvt_pk_bf16_f32 v66, v70, v71
	v_cvt_pk_bf16_f32 v67, v74, v75
	v_cvt_pk_bf16_f32 v68, v72, v73
	v_cvt_pk_bf16_f32 v69, v76, v77
	s_add_i32 s19, s19, 1
	s_add_i32 s10, s10, 1
	s_cmp_lt_i32 s19, 26
	v_mfma_f32_32x32x16_bf16 v[18:33], v[166:169], v[66:69], v[18:33]
	s_cselect_b64 s[4:5], -1, 0
	s_cmp_lt_i32 s14, 10
	s_cselect_b64 s[0:1], -1, 0
	s_or_b64 s[4:5], s[4:5], s[0:1]
	s_and_b64 vcc, exec, s[4:5]
	v_mfma_f32_32x32x16_bf16 v[34:49], v[170:173], v[66:69], v[34:49]
	v_mfma_f32_32x32x16_bf16 v[50:65], v[154:157], v[66:69], v[50:65]
	s_cbranch_vccz .LBB0_327
	s_branch .LBB0_251

; __device__ __forceinline__ void attn_task(const AttnP& P, LAS unsigned char* lds, int b, int hd, int qq, int c, float shift, int lane_in) {
;     ...
;         } else {
;             attn_load_k(P, lds, hb, li, c, R0, lane, kf); attn_load_v(P, lds, hb, li, c, R0, lane, vf);
;             const int dl = c - (li - 10);
;             if (dl == 0) { w0 = 3 * Hp[0] - Hn[0] + Bn[0]; w1 = 3 * Hp[1] - Hn[1] + Bn[1]; }
;             else if (dl > 0) { const unsigned long long m = ((dl & 3) == 0) ? ~0ull : 0ull; w0 = Bp[0] + (Hp[0] & m); w1 = Bp[1] + (Hp[1] & m); }
;             else { const unsigned long long m = ((dl & 3) == 0) ? ~0ull : 0ull; w0 = Bn[0] + (Hn[0] & m); w1 = Bn[1] + (Hn[1] & m); }
;             ++li; ++ph;
;         }
.LBB0_337:
	s_andn2_b64 vcc, exec, s[4:5]
	s_cbranch_vccnz .LBB0_342
	s_branch .Lal_tile_a3
	s_cmp_gt_i32 s66, 9
	s_cselect_b64 s[0:1], -1, 0
	s_mov_b64 s[4:5], -1
	s_and_b64 vcc, exec, s[0:1]
	s_cbranch_vccz .LBB0_373
	v_lshl_add_u32 v66, s66, 5, v234
	v_mad_u64_u32 v[70:71], s[4:5], v66, s71, v[200:201]
	ds_read_b128 v[66:69], v70
	ds_read_b128 v[178:181], v70 offset:32
	ds_read_b128 v[174:177], v70 offset:64
	ds_read_b128 v[182:185], v70 offset:96
	s_cbranch_execz .LBB0_374

; __device__ __forceinline__ void tile_compute(const bf16x8 (&kf)[4], const bf16x8 (&vf)[2][2], const bf16x8 (&qf)[4], unsigned long long w0, unsigned long long w1,
;                                              float shift, f32x16& o0, f32x16& o1, f32x16& zacc, const bf16x8& ones) {
;     f32x16 st = {};
; #pragma unroll
;     for (int kk = 0; kk < 4; ++kk) st = __builtin_amdgcn_mfma_f32_32x32x16_bf16(kf[kk], qf[kk], st, 0, 0, 0);
;     if (__builtin_amdgcn_readfirstlane(__builtin_bit_cast(int, shift)) != 0) {
;         asm volatile("" ::: "memory");
; #pragma unroll
;         for (int e = 0; e < 16; ++e) st[e] -= shift;
;     }
;     unsigned pw[8];
; #pragma unroll
;     for (int eg = 0; eg < 2; ++eg) {
;         const unsigned long long w = eg ? w1 : w0;
;         const unsigned wl = (unsigned)w, wh = (unsigned)(w >> 32);
;         float pv[8];
; #pragma unroll
;         for (int p = 0; p < 4; ++p) {
;             pv[p] = (float)((wl >> (8 * p)) & 0xffu) * __builtin_amdgcn_exp2f(st[8 * eg + p]);
;             pv[4 + p] = (float)((wh >> (8 * p)) & 0xffu) * __builtin_amdgcn_exp2f(st[8 * eg + 4 + p]);
;         }
; #pragma unroll
;         for (int p = 0; p < 4; ++p) pw[4 * eg + p] = pk2(pv[2 * p], pv[2 * p + 1]);
;     }
;     const bf16x8 pf0 = __builtin_bit_cast(bf16x8, (u32x4){pw[0], pw[1], pw[2], pw[3]});
;     const bf16x8 pf1 = __builtin_bit_cast(bf16x8, (u32x4){pw[4], pw[5], pw[6], pw[7]});
;     o0 = __builtin_amdgcn_mfma_f32_32x32x16_bf16(vf[0][0], pf0, o0, 0, 0, 0);
;     o1 = __builtin_amdgcn_mfma_f32_32x32x16_bf16(vf[1][0], pf0, o1, 0, 0, 0);
;     zacc = __builtin_amdgcn_mfma_f32_32x32x16_bf16(ones, pf0, zacc, 0, 0, 0);
;     o0 = __builtin_amdgcn_mfma_f32_32x32x16_bf16(vf[0][1], pf1, o0, 0, 0, 0);
;     o1 = __builtin_amdgcn_mfma_f32_32x32x16_bf16(vf[1][1], pf1, o1, 0, 0, 0);
;     zacc = __builtin_amdgcn_mfma_f32_32x32x16_bf16(ones, pf1, zacc, 0, 0, 0);
; }
; __device__ __forceinline__ void attn_task(const AttnP& P, LAS unsigned char* lds, int b, int hd, int qq, int c, float shift, int lane_in) {
;     ...
;             attn_load_k(P, lds, hb, li, c, R0, lane, kf); attn_load_v(P, lds, hb, li, c, R0, lane, vf);
;             const int dl = c - (li - 10);
;             if (dl == 0) { w0 = 3 * Hp[0] - Hn[0] + Bn[0]; w1 = 3 * Hp[1] - Hn[1] + Bn[1]; }
.LBB0_428:
	s_waitcnt vmcnt(3) lgkmcnt(3)
	v_mfma_f32_32x32x16_bf16 v[66:81], v[66:69], v[86:89], 0
	v_readfirstlane_b32 s0, v2
	s_nop 1
	v_cmp_class_f32_e64 s[0:1], s0, 64
	s_and_b64 vcc, exec, s[0:1]
	s_waitcnt vmcnt(2) lgkmcnt(2)
	v_mfma_f32_32x32x16_bf16 v[66:81], v[178:181], v[90:93], v[66:81]
	s_waitcnt vmcnt(1) lgkmcnt(1)
	v_mfma_f32_32x32x16_bf16 v[66:81], v[174:177], v[94:97], v[66:81]
	s_waitcnt vmcnt(0) lgkmcnt(0)
	v_mfma_f32_32x32x16_bf16 v[66:81], v[182:185], v[98:101], v[66:81]
	s_cbranch_vccnz .LBB0_334
	s_nop 10
	v_sub_f32_e32 v81, v81, v2
	v_sub_f32_e32 v80, v80, v2
	v_sub_f32_e32 v79, v79, v2
	v_sub_f32_e32 v78, v78, v2
	v_sub_f32_e32 v77, v77, v2
	v_sub_f32_e32 v76, v76, v2
	v_sub_f32_e32 v75, v75, v2
	v_sub_f32_e32 v74, v74, v2
	v_sub_f32_e32 v73, v73, v2
	v_sub_f32_e32 v72, v72, v2
	v_sub_f32_e32 v71, v71, v2
	v_sub_f32_e32 v70, v70, v2
	v_sub_f32_e32 v69, v69, v2
	v_sub_f32_e32 v68, v68, v2
	v_sub_f32_e32 v67, v67, v2
	v_sub_f32_e32 v66, v66, v2
	s_branch .LBB0_334
.Lal_tile_a3:
	v_readfirstlane_b32 s75, v2
	s_cmp_lg_u32 s66, 10
	s_cbranch_scc1 .Lal_havek_a3
	s_waitcnt vmcnt(0)
	v_lshl_add_u32 v12, s66, 5, v234
	v_mad_u32_u24 v12, v12, s71, v200
	ds_read_b128 v[244:247], v12
	ds_read_b128 v[248:251], v12 offset:32
	ds_read_b128 v[252:255], v12 offset:64
	ds_read_b128 v[236:239], v12 offset:96
.Lal_havek_a3:
	s_lshl_b32 s74, s66, 12
	v_add3_u32 v13, v233, s74, v226
	s_add_i32 s82, s92, 10
	s_and_b32 s75, s75, 0x7fffffff
	s_sub_i32 s73, s82, s66
	s_cmp_gt_i32 s73, 0
	s_cselect_b64 s[76:77], -1, 0
	s_and_b32 s74, s73, 3
	s_cmp_eq_u32 s74, 0
	s_cselect_b64 s[78:79], -1, 0
	s_cmp_eq_u32 s73, 0
	s_cselect_b64 s[80:81], -1, 0
	s_add_i32 s83, s66, 1
	s_waitcnt lgkmcnt(0)
	v_mfma_f32_32x32x16_bf16 v[66:81], v[244:247], v[86:89], 0
	v_mfma_f32_32x32x16_bf16 v[66:81], v[248:251], v[90:93], v[66:81]
	v_mfma_f32_32x32x16_bf16 v[66:81], v[252:255], v[94:97], v[66:81]
	v_mfma_f32_32x32x16_bf16 v[66:81], v[236:239], v[98:101], v[66:81]
	ds_read_b128 v[162:165], v13
	ds_read_b128 v[158:161], v13 offset:512
	ds_read_b128 v[166:169], v13 offset:2048
	ds_read_b128 v[170:173], v13 offset:2560
	v_lshl_add_u32 v12, s83, 5, v234
	v_mad_u32_u24 v12, v12, s71, v200
	ds_read_b128 v[244:247], v12
	ds_read_b128 v[248:251], v12 offset:32
	ds_read_b128 v[252:255], v12 offset:64
	ds_read_b128 v[236:239], v12 offset:96
	v_cndmask_b32_e64 v4, v122, v118, s[76:77]
	v_cndmask_b32_e64 v5, v123, v119, s[76:77]
	v_cndmask_b32_e64 v6, v124, v120, s[76:77]
	v_cndmask_b32_e64 v7, v125, v121, s[76:77]
	v_cndmask_b32_e64 v8, v130, v126, s[76:77]
	v_cndmask_b32_e64 v9, v131, v127, s[76:77]
	v_cndmask_b32_e64 v10, v132, v128, s[76:77]
	v_cndmask_b32_e64 v11, v133, v129, s[76:77]
	v_cndmask_b32_e64 v4, 0, v4, s[78:79]
	v_cndmask_b32_e64 v5, 0, v5, s[78:79]
	v_cndmask_b32_e64 v6, 0, v6, s[78:79]
	v_cndmask_b32_e64 v7, 0, v7, s[78:79]
	v_lshl_add_u64 v[212:213], v[4:5], 0, v[8:9]
	v_lshl_add_u64 v[210:211], v[6:7], 0, v[10:11]
	v_cndmask_b32_e64 v212, v212, v202, s[80:81]
	v_cndmask_b32_e64 v213, v213, v203, s[80:81]
	v_cndmask_b32_e64 v210, v210, v204, s[80:81]
	v_cndmask_b32_e64 v211, v211, v205, s[80:81]
	s_cmp_lg_u32 s75, 0
	s_cbranch_scc1 .Lal_shift_a3
.Lal_noshift_a3:
	v_exp_f32_e32 v66, v66
	v_exp_f32_e32 v67, v67
	v_exp_f32_e32 v70, v70
	v_exp_f32_e32 v71, v71
	v_exp_f32_e32 v68, v68
	v_exp_f32_e32 v69, v69
	v_cvt_f32_ubyte1_e32 v175, v212
	v_cvt_f32_ubyte0_e32 v174, v212
	v_exp_f32_e32 v72, v72
	v_exp_f32_e32 v73, v73
	v_pk_mul_f32 v[66:67], v[66:67], v[174:175]
	v_cvt_f32_ubyte1_e32 v175, v213
	v_cvt_f32_ubyte0_e32 v174, v213
	v_pk_mul_f32 v[70:71], v[70:71], v[174:175]
	v_cvt_f32_ubyte3_e32 v175, v212
	v_cvt_f32_ubyte2_e32 v174, v212
	v_pk_mul_f32 v[68:69], v[68:69], v[174:175]
	v_cvt_f32_ubyte3_e32 v175, v213
	v_cvt_f32_ubyte2_e32 v174, v213
	v_pk_mul_f32 v[72:73], v[72:73], v[174:175]
	v_cvt_pk_bf16_f32 v66, v66, v67
	v_cvt_pk_bf16_f32 v67, v68, v69
	v_cvt_pk_bf16_f32 v68, v70, v71
	v_exp_f32_e32 v70, v74
	v_exp_f32_e32 v71, v75
	v_cvt_pk_bf16_f32 v69, v72, v73
	v_exp_f32_e32 v72, v78
	v_exp_f32_e32 v73, v79
	s_waitcnt lgkmcnt(4)
	v_mfma_f32_32x32x16_bf16 v[18:33], v[162:165], v[66:69], v[18:33]
	v_cvt_f32_ubyte1_e32 v75, v210
	v_cvt_f32_ubyte0_e32 v74, v210
	v_mul_f32_e64 v70, v70, v74
	v_mul_f32_e64 v71, v71, v75
	v_cvt_f32_ubyte1_e32 v75, v211
	v_cvt_f32_ubyte0_e32 v74, v211
	v_pk_mul_f32 v[72:73], v[72:73], v[74:75]
	v_exp_f32_e32 v74, v76
	v_mfma_f32_32x32x16_bf16 v[34:49], v[158:161], v[66:69], v[34:49]
	v_exp_f32_e32 v75, v77
	v_exp_f32_e32 v76, v80
	v_exp_f32_e32 v77, v81
	v_cvt_f32_ubyte3_e32 v79, v210
	v_cvt_f32_ubyte2_e32 v78, v210
	v_pk_mul_f32 v[74:75], v[74:75], v[78:79]
	v_mfma_f32_32x32x16_bf16 v[50:65], v[154:157], v[66:69], v[50:65]
	v_cvt_f32_ubyte3_e32 v67, v211
	v_cvt_f32_ubyte2_e32 v66, v211
	v_mul_f32_e64 v76, v76, v66
	v_mul_f32_e64 v77, v77, v67
	v_cvt_pk_bf16_f32 v66, v70, v71
	v_cvt_pk_bf16_f32 v67, v74, v75
	v_cvt_pk_bf16_f32 v68, v72, v73
	v_cvt_pk_bf16_f32 v69, v76, v77
	s_add_i32 s66, s66, 1
	s_add_i32 s8, s8, 1
	s_cmp_lt_i32 s66, 26
	v_mfma_f32_32x32x16_bf16 v[18:33], v[166:169], v[66:69], v[18:33]
	s_cselect_b64 s[4:5], -1, 0
	s_cmp_lt_i32 s72, 10
	s_cselect_b64 s[0:1], -1, 0
	s_or_b64 s[4:5], s[4:5], s[0:1]
	s_and_b64 vcc, exec, s[4:5]
	v_mfma_f32_32x32x16_bf16 v[34:49], v[170:173], v[66:69], v[34:49]
	v_mfma_f32_32x32x16_bf16 v[50:65], v[154:157], v[66:69], v[50:65]
	s_cbranch_vccz .LBB0_430
	s_branch .LBB0_335

; __device__ __forceinline__ void attn_task(const AttnP& P, LAS unsigned char* lds, int b, int hd, int qq, int c, float shift, int lane_in) {
;     ...
;         } else {
;             attn_load_k(P, lds, hb, li, c, R0, lane, kf); attn_load_v(P, lds, hb, li, c, R0, lane, vf);
;             const int dl = c - (li - 10);
;             if (dl == 0) { w0 = 3 * Hp[0] - Hn[0] + Bn[0]; w1 = 3 * Hp[1] - Hn[1] + Bn[1]; }
;             else if (dl > 0) { const unsigned long long m = ((dl & 3) == 0) ? ~0ull : 0ull; w0 = Bp[0] + (Hp[0] & m); w1 = Bp[1] + (Hp[1] & m); }
;             else { const unsigned long long m = ((dl & 3) == 0) ? ~0ull : 0ull; w0 = Bn[0] + (Hn[0] & m); w1 = Bn[1] + (Hn[1] & m); }
;             ++li; ++ph;
;         }
.LBB0_440:
	s_andn2_b64 vcc, exec, s[4:5]
	s_cbranch_vccnz .LBB0_445
	s_branch .Lal_tile_a4
	s_cmp_gt_i32 s56, 9
	s_cselect_b64 s[0:1], -1, 0
	s_mov_b64 s[4:5], -1
	s_and_b64 vcc, exec, s[0:1]
	s_cbranch_vccz .LBB0_476
	v_lshl_add_u32 v66, s56, 5, v234
	v_mad_u64_u32 v[70:71], s[4:5], v66, s71, v[200:201]
	ds_read_b128 v[66:69], v70
	ds_read_b128 v[178:181], v70 offset:32
	ds_read_b128 v[174:177], v70 offset:64
	ds_read_b128 v[182:185], v70 offset:96
	s_cbranch_execz .LBB0_477

; __device__ __forceinline__ void tile_compute(const bf16x8 (&kf)[4], const bf16x8 (&vf)[2][2], const bf16x8 (&qf)[4], unsigned long long w0, unsigned long long w1,
;                                              float shift, f32x16& o0, f32x16& o1, f32x16& zacc, const bf16x8& ones) {
;     f32x16 st = {};
; #pragma unroll
;     for (int kk = 0; kk < 4; ++kk) st = __builtin_amdgcn_mfma_f32_32x32x16_bf16(kf[kk], qf[kk], st, 0, 0, 0);
;     if (__builtin_amdgcn_readfirstlane(__builtin_bit_cast(int, shift)) != 0) {
;         asm volatile("" ::: "memory");
; #pragma unroll
;         for (int e = 0; e < 16; ++e) st[e] -= shift;
;     }
;     unsigned pw[8];
; #pragma unroll
;     for (int eg = 0; eg < 2; ++eg) {
;         const unsigned long long w = eg ? w1 : w0;
;         const unsigned wl = (unsigned)w, wh = (unsigned)(w >> 32);
;         float pv[8];
; #pragma unroll
;         for (int p = 0; p < 4; ++p) {
;             pv[p] = (float)((wl >> (8 * p)) & 0xffu) * __builtin_amdgcn_exp2f(st[8 * eg + p]);
;             pv[4 + p] = (float)((wh >> (8 * p)) & 0xffu) * __builtin_amdgcn_exp2f(st[8 * eg + 4 + p]);
;         }
; #pragma unroll
;         for (int p = 0; p < 4; ++p) pw[4 * eg + p] = pk2(pv[2 * p], pv[2 * p + 1]);
;     }
;     const bf16x8 pf0 = __builtin_bit_cast(bf16x8, (u32x4){pw[0], pw[1], pw[2], pw[3]});
;     const bf16x8 pf1 = __builtin_bit_cast(bf16x8, (u32x4){pw[4], pw[5], pw[6], pw[7]});
;     o0 = __builtin_amdgcn_mfma_f32_32x32x16_bf16(vf[0][0], pf0, o0, 0, 0, 0);
;     o1 = __builtin_amdgcn_mfma_f32_32x32x16_bf16(vf[1][0], pf0, o1, 0, 0, 0);
;     zacc = __builtin_amdgcn_mfma_f32_32x32x16_bf16(ones, pf0, zacc, 0, 0, 0);
;     o0 = __builtin_amdgcn_mfma_f32_32x32x16_bf16(vf[0][1], pf1, o0, 0, 0, 0);
;     o1 = __builtin_amdgcn_mfma_f32_32x32x16_bf16(vf[1][1], pf1, o1, 0, 0, 0);
;     zacc = __builtin_amdgcn_mfma_f32_32x32x16_bf16(ones, pf1, zacc, 0, 0, 0);
; }
; __device__ __forceinline__ void attn_task(const AttnP& P, LAS unsigned char* lds, int b, int hd, int qq, int c, float shift, int lane_in) {
;     ...
;             attn_load_k(P, lds, hb, li, c, R0, lane, kf); attn_load_v(P, lds, hb, li, c, R0, lane, vf);
;             const int dl = c - (li - 10);
;             if (dl == 0) { w0 = 3 * Hp[0] - Hn[0] + Bn[0]; w1 = 3 * Hp[1] - Hn[1] + Bn[1]; }
.Lal_tile_a4:
	v_readfirstlane_b32 s75, v2
	s_cmp_lg_u32 s56, 10
	s_cbranch_scc1 .Lal_havek_a4
	s_waitcnt vmcnt(0)
	v_lshl_add_u32 v12, s56, 5, v234
	v_mad_u32_u24 v12, v12, s71, v200
	ds_read_b128 v[244:247], v12
	ds_read_b128 v[248:251], v12 offset:32
	ds_read_b128 v[252:255], v12 offset:64
	ds_read_b128 v[236:239], v12 offset:96
.Lal_havek_a4:
	s_lshl_b32 s74, s56, 12
	v_add3_u32 v13, v233, s74, v228
	s_add_i32 s82, s64, 10
	s_and_b32 s75, s75, 0x7fffffff
	s_sub_i32 s73, s82, s56
	s_cmp_gt_i32 s73, 0
	s_cselect_b64 s[76:77], -1, 0
	s_and_b32 s74, s73, 3
	s_cmp_eq_u32 s74, 0
	s_cselect_b64 s[78:79], -1, 0
	s_cmp_eq_u32 s73, 0
	s_cselect_b64 s[80:81], -1, 0
	s_add_i32 s83, s56, 1
	s_waitcnt lgkmcnt(0)
	v_mfma_f32_32x32x16_bf16 v[66:81], v[244:247], v[86:89], 0
	v_mfma_f32_32x32x16_bf16 v[66:81], v[248:251], v[90:93], v[66:81]
	v_mfma_f32_32x32x16_bf16 v[66:81], v[252:255], v[94:97], v[66:81]
	v_mfma_f32_32x32x16_bf16 v[66:81], v[236:239], v[98:101], v[66:81]
	ds_read_b128 v[162:165], v13
	ds_read_b128 v[158:161], v13 offset:512
	ds_read_b128 v[166:169], v13 offset:2048
	ds_read_b128 v[170:173], v13 offset:2560
	v_lshl_add_u32 v12, s83, 5, v234
	v_mad_u32_u24 v12, v12, s71, v200
	ds_read_b128 v[244:247], v12
	ds_read_b128 v[248:251], v12 offset:32
	ds_read_b128 v[252:255], v12 offset:64
	ds_read_b128 v[236:239], v12 offset:96
	v_cndmask_b32_e64 v4, v122, v118, s[76:77]
	v_cndmask_b32_e64 v5, v123, v119, s[76:77]
	v_cndmask_b32_e64 v6, v124, v120, s[76:77]
	v_cndmask_b32_e64 v7, v125, v121, s[76:77]
	v_cndmask_b32_e64 v8, v130, v126, s[76:77]
	v_cndmask_b32_e64 v9, v131, v127, s[76:77]
	v_cndmask_b32_e64 v10, v132, v128, s[76:77]
	v_cndmask_b32_e64 v11, v133, v129, s[76:77]
	v_cndmask_b32_e64 v4, 0, v4, s[78:79]
	v_cndmask_b32_e64 v5, 0, v5, s[78:79]
	v_cndmask_b32_e64 v6, 0, v6, s[78:79]
	v_cndmask_b32_e64 v7, 0, v7, s[78:79]
	v_lshl_add_u64 v[212:213], v[4:5], 0, v[8:9]
	v_lshl_add_u64 v[210:211], v[6:7], 0, v[10:11]
	v_cndmask_b32_e64 v212, v212, v202, s[80:81]
	v_cndmask_b32_e64 v213, v213, v203, s[80:81]
	v_cndmask_b32_e64 v210, v210, v204, s[80:81]
	v_cndmask_b32_e64 v211, v211, v205, s[80:81]
	s_cmp_lg_u32 s75, 0
	s_cbranch_scc1 .Lal_shift_a4
.Lal_noshift_a4:
	v_exp_f32_e32 v66, v66
	v_exp_f32_e32 v67, v67
	v_exp_f32_e32 v70, v70
	v_exp_f32_e32 v71, v71
	v_exp_f32_e32 v68, v68
	v_exp_f32_e32 v69, v69
	v_cvt_f32_ubyte1_e32 v175, v212
	v_cvt_f32_ubyte0_e32 v174, v212
	v_exp_f32_e32 v72, v72
	v_exp_f32_e32 v73, v73
	v_pk_mul_f32 v[66:67], v[66:67], v[174:175]
	v_cvt_f32_ubyte1_e32 v175, v213
	v_cvt_f32_ubyte0_e32 v174, v213
	v_pk_mul_f32 v[70:71], v[70:71], v[174:175]
	v_cvt_f32_ubyte3_e32 v175, v212
	v_cvt_f32_ubyte2_e32 v174, v212
	v_pk_mul_f32 v[68:69], v[68:69], v[174:175]
	v_cvt_f32_ubyte3_e32 v175, v213
	v_cvt_f32_ubyte2_e32 v174, v213
	v_pk_mul_f32 v[72:73], v[72:73], v[174:175]
	v_cvt_pk_bf16_f32 v66, v66, v67
	v_cvt_pk_bf16_f32 v67, v68, v69
	v_cvt_pk_bf16_f32 v68, v70, v71
	v_exp_f32_e32 v70, v74
	v_exp_f32_e32 v71, v75
	v_cvt_pk_bf16_f32 v69, v72, v73
	v_exp_f32_e32 v72, v78
	v_exp_f32_e32 v73, v79
	s_waitcnt lgkmcnt(4)
	v_mfma_f32_32x32x16_bf16 v[18:33], v[162:165], v[66:69], v[18:33]
	v_cvt_f32_ubyte1_e32 v75, v210
	v_cvt_f32_ubyte0_e32 v74, v210
	v_mul_f32_e64 v70, v70, v74
	v_mul_f32_e64 v71, v71, v75
	v_cvt_f32_ubyte1_e32 v75, v211
	v_cvt_f32_ubyte0_e32 v74, v211
	v_pk_mul_f32 v[72:73], v[72:73], v[74:75]
	v_exp_f32_e32 v74, v76
	v_mfma_f32_32x32x16_bf16 v[34:49], v[158:161], v[66:69], v[34:49]
	v_exp_f32_e32 v75, v77
	v_exp_f32_e32 v76, v80
	v_exp_f32_e32 v77, v81
	v_cvt_f32_ubyte3_e32 v79, v210
	v_cvt_f32_ubyte2_e32 v78, v210
	v_pk_mul_f32 v[74:75], v[74:75], v[78:79]
	v_mfma_f32_32x32x16_bf16 v[50:65], v[154:157], v[66:69], v[50:65]
	v_cvt_f32_ubyte3_e32 v67, v211
	v_cvt_f32_ubyte2_e32 v66, v211
	v_mul_f32_e64 v76, v76, v66
	v_mul_f32_e64 v77, v77, v67
	v_cvt_pk_bf16_f32 v66, v70, v71
	v_cvt_pk_bf16_f32 v67, v74, v75
	v_cvt_pk_bf16_f32 v68, v72, v73
	v_cvt_pk_bf16_f32 v69, v76, v77
	s_add_i32 s56, s56, 1
	s_add_i32 s8, s8, 1
	s_cmp_lt_i32 s56, 26
	v_mfma_f32_32x32x16_bf16 v[18:33], v[166:169], v[66:69], v[18:33]
	s_cselect_b64 s[4:5], -1, 0
	s_cmp_lt_i32 s24, 10
	s_cselect_b64 s[0:1], -1, 0
	s_or_b64 s[4:5], s[4:5], s[0:1]
	s_and_b64 vcc, exec, s[4:5]
	v_mfma_f32_32x32x16_bf16 v[34:49], v[170:173], v[66:69], v[34:49]
	v_mfma_f32_32x32x16_bf16 v[50:65], v[154:157], v[66:69], v[50:65]
	s_cbranch_vccz .LBB0_533
	s_branch .LBB0_438

; __global__ void __launch_bounds__(512, 2) mk_fwd(Args args) {
	.amdhsa_kernel _Z6mk_fwd4Args
		.amdhsa_group_segment_fixed_size 0
		.amdhsa_private_segment_fixed_size 0
		.amdhsa_kernarg_size 392
		.amdhsa_user_sgpr_count 2
		.amdhsa_user_sgpr_dispatch_ptr 0
		.amdhsa_user_sgpr_queue_ptr 0
		.amdhsa_user_sgpr_kernarg_segment_ptr 1
		.amdhsa_user_sgpr_dispatch_id 0
		.amdhsa_user_sgpr_kernarg_preload_length 0
		.amdhsa_user_sgpr_kernarg_preload_offset 0
		.amdhsa_user_sgpr_private_segment_size 0
		.amdhsa_uses_dynamic_stack 0
		.amdhsa_enable_private_segment 0
		.amdhsa_system_sgpr_workgroup_id_x 1
		.amdhsa_system_sgpr_workgroup_id_y 0
		.amdhsa_system_sgpr_workgroup_id_z 0
		.amdhsa_system_sgpr_workgroup_info 0
		.amdhsa_system_vgpr_workitem_id 0
		.amdhsa_next_free_vgpr 256
		.amdhsa_next_free_sgpr 102
		.amdhsa_accum_offset 256
		.amdhsa_reserve_vcc 1
		.amdhsa_float_round_mode_32 0
		.amdhsa_float_round_mode_16_64 0
		.amdhsa_float_denorm_mode_32 3
		.amdhsa_float_denorm_mode_16_64 3
		.amdhsa_dx10_clamp 1
		.amdhsa_ieee_mode 1
		.amdhsa_fp16_overflow 0
		.amdhsa_tg_split 0
		.amdhsa_exception_fp_ieee_invalid_op 0
		.amdhsa_exception_fp_denorm_src 0
		.amdhsa_exception_fp_ieee_div_zero 0
		.amdhsa_exception_fp_ieee_overflow 0
		.amdhsa_exception_fp_ieee_underflow 0
		.amdhsa_exception_fp_ieee_inexact 0
		.amdhsa_exception_int_div_zero 0
	.end_amdhsa_kernel

; __global__ void __launch_bounds__(512, 2) mk_fwd(Args args) {
amdhsa.kernels:
  - .agpr_count:     0
    .args:
      - .offset:         0
        .size:           136
        .value_kind:     by_value
      - .offset:         136
        .size:           4
        .value_kind:     hidden_block_count_x
      - .offset:         140
        .size:           4
        .value_kind:     hidden_block_count_y
      - .offset:         144
        .size:           4
        .value_kind:     hidden_block_count_z
      - .offset:         148
        .size:           2
        .value_kind:     hidden_group_size_x
      - .offset:         150
        .size:           2
        .value_kind:     hidden_group_size_y
      - .offset:         152
        .size:           2
        .value_kind:     hidden_group_size_z
      - .offset:         154
        .size:           2
        .value_kind:     hidden_remainder_x
      - .offset:         156
        .size:           2
        .value_kind:     hidden_remainder_y
      - .offset:         158
        .size:           2
        .value_kind:     hidden_remainder_z
      - .offset:         176
        .size:           8
        .value_kind:     hidden_global_offset_x
      - .offset:         184
        .size:           8
        .value_kind:     hidden_global_offset_y
      - .offset:         192
        .size:           8
        .value_kind:     hidden_global_offset_z
      - .offset:         200
        .size:           2
        .value_kind:     hidden_grid_dims
      - .offset:         256
        .size:           4
        .value_kind:     hidden_dynamic_lds_size
    .group_segment_fixed_size: 0
    .kernarg_segment_align: 8
    .kernarg_segment_size: 392
    .language:       OpenCL C
    .language_version:
      - 2
      - 0
    .max_flat_workgroup_size: 512
    .name:           _Z6mk_fwd4Args
    .private_segment_fixed_size: 0
    .sgpr_count:     108
    .sgpr_spill_count: 76
    .symbol:         _Z6mk_fwd4Args.kd
    .uniform_work_group_size: 1
    .uses_dynamic_stack: false
    .vgpr_count:     256
    .vgpr_spill_count: 0
    .wavefront_size: 64
